# attention: packed f32 adds in the tile exp / row-sum code split into scalar adds
# speedup vs baseline: 1.0070x; 1.0070x over previous
.LBB0_458:
	v_max3_f32 v2, v48, v49, v32
	v_max3_f32 v3, v50, v51, v33
	v_mov_b32_e32 v64, 0
	v_max3_f32 v2, v2, v34, v35
	v_max3_f32 v3, v3, v54, v55
	s_nop 0
	v_max3_f32 v2, v2, v52, v53
	v_max3_f32 v3, v3, v38, v39
	s_nop 0
	v_max3_f32 v2, v2, v36, v37
	v_max3_f32 v3, v3, v58, v59
	s_nop 0
	v_max3_f32 v2, v2, v56, v57
	v_max3_f32 v3, v3, v42, v43
	s_nop 0
	v_max3_f32 v2, v2, v40, v41
	v_max3_f32 v3, v3, v62, v63
	s_nop 0
	v_max3_f32 v2, v2, v60, v61
	v_max3_f32 v3, v3, v46, v47
	s_nop 0
	v_max3_f32 v2, v2, v44, v45
	v_max_f32_e32 v3, v3, v3
	v_max_f32_e32 v2, v2, v2
	v_max_f32_e32 v2, v2, v3
	v_mov_b32_e32 v3, v2
	s_nop 1
	v_permlane32_swap_b32_e32 v2, v3
	v_max_f32_e32 v3, v3, v3
	v_max_f32_e32 v2, v2, v2
	v_max_f32_e32 v2, v2, v3
	v_cmp_neq_f32_e32 vcc, 0, v2
	s_cbranch_vccz .LBB0_461
	v_exp_f32_e64 v3, -v2
	v_add_f32_e32 v153, 0, v2
	v_sub_f32_e32 v48, v48, v2
	v_sub_f32_e32 v49, v49, v2
	v_sub_f32_e32 v32, v32, v2
	v_sub_f32_e32 v33, v33, v2
	v_sub_f32_e32 v50, v50, v2
	v_sub_f32_e32 v51, v51, v2
	v_mul_f32_e32 v64, 0, v3
	v_sub_f32_e32 v34, v34, v2
	v_sub_f32_e32 v35, v35, v2
	v_sub_f32_e32 v52, v52, v2
	v_sub_f32_e32 v53, v53, v2
	v_sub_f32_e32 v36, v36, v2
	v_sub_f32_e32 v37, v37, v2
	v_sub_f32_e32 v54, v54, v2
	v_sub_f32_e32 v55, v55, v2
	v_sub_f32_e32 v38, v38, v2
	v_sub_f32_e32 v39, v39, v2
	v_sub_f32_e32 v56, v56, v2
	v_sub_f32_e32 v57, v57, v2
	v_sub_f32_e32 v40, v40, v2
	v_sub_f32_e32 v41, v41, v2
	v_sub_f32_e32 v58, v58, v2
	v_sub_f32_e32 v59, v59, v2
	v_sub_f32_e32 v42, v42, v2
	v_sub_f32_e32 v43, v43, v2
	v_sub_f32_e32 v60, v60, v2
	v_sub_f32_e32 v61, v61, v2
	v_sub_f32_e32 v44, v44, v2
	v_sub_f32_e32 v45, v45, v2
	v_sub_f32_e32 v62, v62, v2
	v_sub_f32_e32 v63, v63, v2
	v_sub_f32_e32 v46, v46, v2
	v_sub_f32_e32 v47, v47, v2
	s_branch .LBB0_462

.LBB0_462:
	v_exp_f32_e32 v2, v48
	v_exp_f32_e32 v3, v49
	v_exp_f32_e32 v158, v50
	v_exp_f32_e32 v159, v51
	v_exp_f32_e32 v52, v52
	v_exp_f32_e32 v53, v53
	v_exp_f32_e32 v54, v54
	v_exp_f32_e32 v55, v55
	v_exp_f32_e32 v154, v32
	v_exp_f32_e32 v155, v33
	v_mov_b32_e32 v65, v64
	v_mov_b32_e32 v66, v64
	v_mov_b32_e32 v67, v64
	v_mov_b32_e32 v68, v64
	v_mov_b32_e32 v69, v64
	v_mov_b32_e32 v70, v64
	v_mov_b32_e32 v71, v64
	v_mov_b32_e32 v72, v64
	v_mov_b32_e32 v73, v64
	v_mov_b32_e32 v74, v64
	v_mov_b32_e32 v75, v64
	v_mov_b32_e32 v76, v64
	v_mov_b32_e32 v77, v64
	v_mov_b32_e32 v78, v64
	v_mov_b32_e32 v79, v64
	v_mov_b32_e32 v4, v2
	v_mov_b32_e32 v5, v3
	v_cvt_pk_bf16_f32 v48, v2, v3
	v_cvt_pk_bf16_f32 v49, v158, v159
	v_cvt_pk_bf16_f32 v50, v52, v53
	v_cvt_pk_bf16_f32 v51, v54, v55
	v_add_f32_e32 v156, v154, v4
	v_add_f32_e32 v157, v155, v5
	v_exp_f32_e32 v56, v56
	s_waitcnt lgkmcnt(7)
	v_mfma_f32_32x32x16_bf16 v[2:17], v[18:21], v[48:51], v[64:79]
	v_mov_b64_e32 v[18:19], v[64:65]
	v_mov_b64_e32 v[20:21], v[66:67]
	v_mov_b64_e32 v[22:23], v[68:69]
	v_mov_b64_e32 v[24:25], v[70:71]
	v_mov_b64_e32 v[26:27], v[72:73]
	v_mov_b64_e32 v[28:29], v[74:75]
	v_mov_b64_e32 v[30:31], v[76:77]
	v_mov_b64_e32 v[32:33], v[78:79]
	v_exp_f32_e32 v57, v57
	v_exp_f32_e32 v58, v58
	s_waitcnt lgkmcnt(5)
	v_mfma_f32_32x32x16_bf16 v[18:33], v[128:131], v[48:51], v[18:33]
	v_exp_f32_e32 v59, v59
	v_exp_f32_e32 v60, v60
	v_exp_f32_e32 v61, v61
	v_exp_f32_e32 v62, v62
	v_exp_f32_e32 v63, v63
	v_cvt_pk_bf16_f32 v48, v56, v57
	v_cvt_pk_bf16_f32 v49, v58, v59
	v_cvt_pk_bf16_f32 v50, v60, v61
	v_cvt_pk_bf16_f32 v51, v62, v63
	v_exp_f32_e32 v160, v34
	v_exp_f32_e32 v161, v35
	v_mfma_f32_32x32x16_bf16 v[2:17], v[124:127], v[48:51], v[2:17]
	v_exp_f32_e32 v36, v36
	v_exp_f32_e32 v37, v37
	v_add_f32_e32 v34, v158, v156
	v_add_f32_e32 v35, v159, v157
	v_exp_f32_e32 v38, v38
	v_exp_f32_e32 v39, v39
	v_add_f32_e32 v34, v160, v34
	v_add_f32_e32 v35, v161, v35
	v_exp_f32_e32 v40, v40
	s_waitcnt lgkmcnt(4)
	v_mfma_f32_32x32x16_bf16 v[18:33], v[120:123], v[48:51], v[18:33]
	v_add_f32_e64 v34, v52, v34
	v_add_f32_e64 v35, v53, v35
	v_exp_f32_e32 v41, v41
	v_add_f32_e32 v34, v36, v34
	v_add_f32_e32 v35, v37, v35
	v_cvt_pk_bf16_f32 v36, v36, v37
	v_add_f32_e32 v48, v54, v34
	v_add_f32_e32 v49, v55, v35
	v_cvt_pk_bf16_f32 v34, v154, v155
	v_cvt_pk_bf16_f32 v35, v160, v161
	v_cvt_pk_bf16_f32 v37, v38, v39
	v_exp_f32_e32 v42, v42
	v_exp_f32_e32 v43, v43
	s_waitcnt lgkmcnt(3)
	v_mfma_f32_32x32x16_bf16 v[2:17], v[116:119], v[34:37], v[2:17]
	v_exp_f32_e32 v44, v44
	v_exp_f32_e32 v45, v45
	v_exp_f32_e32 v46, v46
	v_exp_f32_e32 v47, v47
	v_add_f32_e32 v38, v38, v48
	v_add_f32_e32 v39, v39, v49
	s_nop 0
	v_add_f32_e32 v38, v56, v38
	v_add_f32_e32 v39, v57, v39
	s_waitcnt lgkmcnt(1)
	v_mfma_f32_32x32x16_bf16 v[18:33], v[112:115], v[34:37], v[18:33]
	v_cvt_pk_bf16_f32 v34, v40, v41
	v_cvt_pk_bf16_f32 v35, v42, v43
	v_cvt_pk_bf16_f32 v36, v44, v45
	v_cvt_pk_bf16_f32 v37, v46, v47
	v_add_f32_e64 v38, v40, v38
	v_add_f32_e64 v39, v41, v39
	v_add_f32_e32 v38, v58, v38
	v_add_f32_e32 v39, v59, v39
	v_mfma_f32_32x32x16_bf16 v[2:17], v[108:111], v[34:37], v[2:17]
	v_add_f32_e64 v38, v42, v38
	v_add_f32_e64 v39, v43, v39
	v_add_f32_e64 v38, v60, v38
	v_add_f32_e64 v39, v61, v39
	v_add_f32_e64 v38, v44, v38
	v_add_f32_e64 v39, v45, v39
	v_add_f32_e32 v38, v62, v38
	v_add_f32_e32 v39, v63, v39
	s_waitcnt lgkmcnt(0)
	v_mfma_f32_32x32x16_bf16 v[18:33], v[104:107], v[34:37], v[18:33]
	v_add_f32_e64 v38, v46, v38
	v_add_f32_e64 v39, v47, v39
	v_add_f32_e32 v34, v38, v39
	v_add_f32_e32 v79, v64, v34

.LBB0_464:
	v_exp_f32_e32 v50, v50
	v_exp_f32_e32 v51, v51
	v_exp_f32_e32 v126, v52
	v_exp_f32_e32 v127, v53
	v_exp_f32_e32 v54, v54
	v_exp_f32_e32 v55, v55
	v_exp_f32_e32 v56, v56
	v_exp_f32_e32 v57, v57
	v_mov_b32_e32 v124, v50
	v_mov_b32_e32 v125, v51
	v_cvt_pk_bf16_f32 v50, v50, v51
	v_cvt_pk_bf16_f32 v51, v126, v127
	v_cvt_pk_bf16_f32 v52, v54, v55
	v_cvt_pk_bf16_f32 v53, v56, v57
	v_exp_f32_e32 v58, v58
	v_exp_f32_e32 v59, v59
	s_waitcnt lgkmcnt(7)
	v_mfma_f32_32x32x16_bf16 v[2:17], v[120:123], v[50:53], v[2:17]
	v_exp_f32_e32 v60, v60
	v_exp_f32_e32 v61, v61
	v_exp_f32_e32 v62, v62
	v_exp_f32_e32 v63, v63
	v_exp_f32_e32 v64, v64
	v_exp_f32_e32 v65, v65
	v_exp_f32_e32 v34, v34
	s_waitcnt lgkmcnt(6)
	v_mfma_f32_32x32x16_bf16 v[18:33], v[116:119], v[50:53], v[18:33]
	v_cvt_pk_bf16_f32 v50, v58, v59
	v_cvt_pk_bf16_f32 v51, v60, v61
	v_cvt_pk_bf16_f32 v52, v62, v63
	v_cvt_pk_bf16_f32 v53, v64, v65
	v_exp_f32_e32 v35, v35
	v_exp_f32_e32 v36, v36
	v_exp_f32_e32 v37, v37
	s_waitcnt lgkmcnt(5)
	v_mfma_f32_32x32x16_bf16 v[2:17], v[112:115], v[50:53], v[2:17]
	v_exp_f32_e32 v38, v38
	v_exp_f32_e32 v39, v39
	v_exp_f32_e32 v40, v40
	v_exp_f32_e32 v41, v41
	v_add_f32_e32 v120, v34, v124
	v_add_f32_e32 v121, v35, v125
	v_cvt_pk_bf16_f32 v34, v34, v35
	v_add_f32_e32 v112, v126, v120
	v_add_f32_e32 v113, v127, v121
	s_waitcnt lgkmcnt(4)
	v_mfma_f32_32x32x16_bf16 v[18:33], v[108:111], v[50:53], v[18:33]
	v_add_f32_e64 v112, v36, v112
	v_add_f32_e64 v113, v37, v113
	v_cvt_pk_bf16_f32 v35, v36, v37
	v_cvt_pk_bf16_f32 v36, v38, v39
	v_cvt_pk_bf16_f32 v37, v40, v41
	v_add_f32_e32 v54, v54, v112
	v_add_f32_e32 v55, v55, v113
	s_nop 0
	v_add_f32_e32 v54, v38, v54
	v_add_f32_e32 v55, v39, v55
	s_waitcnt lgkmcnt(3)
	v_mfma_f32_32x32x16_bf16 v[2:17], v[104:107], v[34:37], v[2:17]
	v_add_f32_e64 v50, v56, v54
	v_add_f32_e64 v51, v57, v55
	v_add_f32_e64 v38, v40, v50
	v_add_f32_e64 v39, v41, v51
	v_exp_f32_e32 v40, v42
	v_exp_f32_e32 v41, v43
	v_exp_f32_e32 v42, v44
	v_exp_f32_e32 v43, v45
	s_waitcnt lgkmcnt(2)
	v_mfma_f32_32x32x16_bf16 v[18:33], v[74:77], v[34:37], v[18:33]
	v_exp_f32_e32 v44, v46
	v_exp_f32_e32 v45, v47
	v_exp_f32_e32 v46, v48
	v_exp_f32_e32 v47, v49
	v_add_f32_e32 v38, v58, v38
	v_add_f32_e32 v39, v59, v39
	v_cvt_pk_bf16_f32 v34, v40, v41
	v_cvt_pk_bf16_f32 v35, v42, v43
	v_cvt_pk_bf16_f32 v36, v44, v45
	v_cvt_pk_bf16_f32 v37, v46, v47
	v_add_f32_e32 v38, v40, v38
	v_add_f32_e32 v39, v41, v39
	s_waitcnt lgkmcnt(1)
	v_mfma_f32_32x32x16_bf16 v[2:17], v[70:73], v[34:37], v[2:17]
	v_add_f32_e64 v38, v60, v38
	v_add_f32_e64 v39, v61, v39
	v_add_f32_e64 v38, v42, v38
	v_add_f32_e64 v39, v43, v39
	v_add_f32_e64 v38, v62, v38
	v_add_f32_e64 v39, v63, v39
	v_add_f32_e32 v38, v44, v38
	v_add_f32_e32 v39, v45, v39
	s_waitcnt lgkmcnt(0)
	v_mfma_f32_32x32x16_bf16 v[18:33], v[66:69], v[34:37], v[18:33]
	v_add_f32_e64 v38, v64, v38
	v_add_f32_e64 v39, v65, v39
	v_add_f32_e64 v38, v46, v38
	v_add_f32_e64 v39, v47, v39
	v_add_f32_e32 v34, v38, v39
	v_add_f32_e32 v79, v79, v34
